# peerq keeps priority 1 through the sub-key score GEMM and drops to 0 only for the top-k selection rounds
# speedup vs baseline: 1.0097x; 1.0054x over previous
; #define MFMA32(a, b, c) __builtin_amdgcn_mfma_f32_32x32x16_bf16((a), (b), (c), 0, 0, 0)
; __device__ void phase_peerq(const Params& p, int bid, int nb, char* lds, const TileMap& tm) {
;     ...
; #pragma unroll
;     for (int j = 0; j < 2; ++j)
; #pragma unroll
;       for (int i = 0; i < 2; ++i)
; #pragma unroll
;         for (int g = 0; g < 4; ++g) {
;           const f32x16& a = acc[j][i];
;           *(uint2*)(qs + (64 * wm + 32 * i + l31) * LDS_ST + 64 * wn + 32 * j + 8 * g + 4 * h) =
;               make_uint2(pack2(a[4 * g], a[4 * g + 1]), pack2(a[4 * g + 2], a[4 * g + 3]));
;         }
; #pragma unroll
;     for (int i = 0; i < 8; ++i) {
;       int c = tid + 256 * i, row = c >> 4, c16 = c & 15;
;       *(uint4*)(ks + row * LDS_ST + c16 * 8) = *(const uint4*)(skb + ((size_t)hp * 128 + row) * 128 + c16 * 8);
;     }
;     __syncthreads();
; #pragma unroll
;     for (int i = 0; i < 2; ++i)
; #pragma unroll
;       for (int j = 0; j < 2; ++j)
; #pragma unroll
;         for (int r = 0; r < 16; ++r) acc[i][j][r] = 0.f;
; #pragma unroll
;     for (int s = 0; s < 8; ++s) {
;       bf16x8 af[2], bfr[2];
; #pragma unroll
;       for (int i = 0; i < 2; ++i) af[i] = *(const bf16x8*)(qs + (64 * wm + 32 * i + l31) * LDS_ST + 16 * s + 8 * h);
; #pragma unroll
;       for (int j = 0; j < 2; ++j) bfr[j] = *(const bf16x8*)(ks + (64 * wn + 32 * j + l31) * LDS_ST + 16 * s + 8 * h);
; #pragma unroll
;       for (int i = 0; i < 2; ++i)
; #pragma unroll
;         for (int j = 0; j < 2; ++j) acc[i][j] = MFMA32(af[i], bfr[j], acc[i][j]);
;     }
.LBB0_453:
	s_nop 4
	v_cvt_pk_bf16_f32 v0, v0, v1
	v_cvt_pk_bf16_f32 v1, v2, v3
	v_cvt_pk_bf16_f32 v2, v4, v5
	v_cvt_pk_bf16_f32 v3, v6, v7
	ds_write2_b64 v85, v[0:1], v[2:3] offset1:2
	v_cvt_pk_bf16_f32 v0, v8, v9
	v_cvt_pk_bf16_f32 v1, v10, v11
	v_cvt_pk_bf16_f32 v2, v12, v13
	v_cvt_pk_bf16_f32 v3, v14, v15
	ds_write2_b64 v85, v[0:1], v[2:3] offset0:4 offset1:6
	v_cvt_pk_bf16_f32 v0, v16, v17
	v_cvt_pk_bf16_f32 v1, v18, v19
	v_cvt_pk_bf16_f32 v2, v20, v21
	v_cvt_pk_bf16_f32 v3, v22, v23
	v_add_u32_e32 v4, 0x2000, v85
	ds_write2_b64 v4, v[0:1], v[2:3] offset0:64 offset1:66
	v_cvt_pk_bf16_f32 v0, v24, v25
	v_cvt_pk_bf16_f32 v1, v26, v27
	v_cvt_pk_bf16_f32 v2, v28, v29
	v_cvt_pk_bf16_f32 v3, v30, v31
	ds_write2_b64 v4, v[0:1], v[2:3] offset0:68 offset1:70
	v_cvt_pk_bf16_f32 v0, v32, v33
	v_cvt_pk_bf16_f32 v1, v34, v35
	v_cvt_pk_bf16_f32 v2, v36, v37
	v_cvt_pk_bf16_f32 v3, v38, v39
	ds_write2_b64 v85, v[0:1], v[2:3] offset0:8 offset1:10
	v_cvt_pk_bf16_f32 v0, v40, v41
	v_cvt_pk_bf16_f32 v1, v42, v43
	v_cvt_pk_bf16_f32 v2, v44, v45
	v_cvt_pk_bf16_f32 v3, v46, v47
	ds_write2_b64 v85, v[0:1], v[2:3] offset0:12 offset1:14
	v_cvt_pk_bf16_f32 v0, v48, v49
	v_cvt_pk_bf16_f32 v1, v50, v51
	v_cvt_pk_bf16_f32 v2, v52, v53
	v_cvt_pk_bf16_f32 v3, v54, v55
	s_ashr_i32 s19, s18, 31
	ds_write2_b64 v4, v[0:1], v[2:3] offset0:72 offset1:74
	v_cvt_pk_bf16_f32 v0, v56, v57
	v_cvt_pk_bf16_f32 v1, v58, v59
	v_cvt_pk_bf16_f32 v2, v60, v61
	v_cvt_pk_bf16_f32 v3, v62, v63
	s_lshl_b64 s[0:1], s[18:19], 15
	ds_write2_b64 v4, v[0:1], v[2:3] offset0:76 offset1:78
	v_lshl_add_u64 v[4:5], v[66:67], 0, s[0:1]
	v_lshl_add_u64 v[0:1], v[4:5], 0, v[68:69]
	global_load_dwordx4 v[0:3], v[0:1], off
	v_add_u32_e32 v64, v95, v98
	s_lshl_b64 s[0:1], s[18:19], 6
	s_add_u32 s0, s92, s0
	s_addc_u32 s1, s93, s1
	s_mov_b64 s[22:23], 0
	s_waitcnt vmcnt(0)
	ds_write_b128 v99, v[0:3]
	v_lshl_add_u64 v[0:1], v[4:5], 0, v[70:71]
	global_load_dwordx4 v[0:3], v[0:1], off
	s_waitcnt vmcnt(0)
	ds_write_b128 v100, v[0:3]
	v_lshl_add_u64 v[0:1], v[4:5], 0, v[72:73]
	global_load_dwordx4 v[0:3], v[0:1], off
	s_waitcnt vmcnt(0)
	ds_write_b128 v101, v[0:3]
	v_lshl_add_u64 v[0:1], v[4:5], 0, v[74:75]
	global_load_dwordx4 v[0:3], v[0:1], off
	s_waitcnt vmcnt(0)
	ds_write_b128 v102, v[0:3]
	v_lshl_add_u64 v[0:1], v[4:5], 0, v[76:77]
	global_load_dwordx4 v[0:3], v[0:1], off
	s_waitcnt vmcnt(0)
	ds_write_b128 v103, v[0:3]
	v_lshl_add_u64 v[0:1], v[4:5], 0, v[78:79]
	global_load_dwordx4 v[0:3], v[0:1], off
	s_waitcnt vmcnt(0)
	ds_write_b128 v104, v[0:3]
	v_lshl_add_u64 v[0:1], v[4:5], 0, v[80:81]
	global_load_dwordx4 v[0:3], v[0:1], off
	s_waitcnt vmcnt(0)
	ds_write_b128 v105, v[0:3]
	v_lshl_add_u64 v[0:1], v[4:5], 0, v[82:83]
	global_load_dwordx4 v[0:3], v[0:1], off
	s_waitcnt vmcnt(0)
	ds_write_b128 v106, v[0:3]
	s_waitcnt lgkmcnt(0)
	s_barrier
	ds_read_b128 v[16:19], v64 offset:8704
	ds_read_b128 v[20:23], v107 offset:43520
	ds_read_b128 v[0:3], v64
	ds_read_b128 v[86:89], v64 offset:32
	ds_read_b128 v[4:7], v107 offset:34816
	ds_read_b128 v[90:93], v107 offset:34848
	s_waitcnt lgkmcnt(1)
	v_mfma_f32_32x32x16_bf16 v[32:47], v[0:3], v[4:7], 0
	ds_read_b128 v[110:113], v64 offset:8736
	ds_read_b128 v[120:123], v107 offset:43552
	v_mfma_f32_32x32x16_bf16 v[48:63], v[0:3], v[20:23], 0
	v_mfma_f32_32x32x16_bf16 v[0:15], v[16:19], v[4:7], 0
	v_mfma_f32_32x32x16_bf16 v[16:31], v[16:19], v[20:23], 0
	s_waitcnt lgkmcnt(2)
	v_mfma_f32_32x32x16_bf16 v[32:47], v[86:89], v[90:93], v[32:47]
	s_waitcnt lgkmcnt(0)
	v_mfma_f32_32x32x16_bf16 v[48:63], v[86:89], v[120:123], v[48:63]
	v_mfma_f32_32x32x16_bf16 v[0:15], v[110:113], v[90:93], v[0:15]
	v_mfma_f32_32x32x16_bf16 v[16:31], v[110:113], v[120:123], v[16:31]
	ds_read_b128 v[86:89], v64 offset:64
	ds_read_b128 v[90:93], v64 offset:8768
	ds_read_b128 v[110:113], v107 offset:34880
	ds_read_b128 v[120:123], v107 offset:43584
	s_waitcnt lgkmcnt(1)
	v_mfma_f32_32x32x16_bf16 v[32:47], v[86:89], v[110:113], v[32:47]
	s_waitcnt lgkmcnt(0)
	v_mfma_f32_32x32x16_bf16 v[48:63], v[86:89], v[120:123], v[48:63]
	v_mfma_f32_32x32x16_bf16 v[0:15], v[90:93], v[110:113], v[0:15]
	v_mfma_f32_32x32x16_bf16 v[16:31], v[90:93], v[120:123], v[16:31]
	ds_read_b128 v[86:89], v64 offset:96
	ds_read_b128 v[90:93], v64 offset:8800
	ds_read_b128 v[110:113], v107 offset:34912
	ds_read_b128 v[120:123], v107 offset:43616
	s_waitcnt lgkmcnt(1)
	v_mfma_f32_32x32x16_bf16 v[32:47], v[86:89], v[110:113], v[32:47]
	s_waitcnt lgkmcnt(0)
	v_mfma_f32_32x32x16_bf16 v[48:63], v[86:89], v[120:123], v[48:63]
	v_mfma_f32_32x32x16_bf16 v[0:15], v[90:93], v[110:113], v[0:15]
	v_mfma_f32_32x32x16_bf16 v[16:31], v[90:93], v[120:123], v[16:31]
	ds_read_b128 v[86:89], v64 offset:128
	ds_read_b128 v[90:93], v64 offset:8832
	ds_read_b128 v[110:113], v107 offset:34944
	ds_read_b128 v[120:123], v107 offset:43648
	s_waitcnt lgkmcnt(1)
	v_mfma_f32_32x32x16_bf16 v[32:47], v[86:89], v[110:113], v[32:47]
	s_waitcnt lgkmcnt(0)
	v_mfma_f32_32x32x16_bf16 v[48:63], v[86:89], v[120:123], v[48:63]
	v_mfma_f32_32x32x16_bf16 v[0:15], v[90:93], v[110:113], v[0:15]
	v_mfma_f32_32x32x16_bf16 v[16:31], v[90:93], v[120:123], v[16:31]
	ds_read_b128 v[86:89], v64 offset:160
	ds_read_b128 v[90:93], v64 offset:8864
	ds_read_b128 v[110:113], v107 offset:34976
	ds_read_b128 v[120:123], v107 offset:43680
	s_waitcnt lgkmcnt(1)
	v_mfma_f32_32x32x16_bf16 v[32:47], v[86:89], v[110:113], v[32:47]
	s_waitcnt lgkmcnt(0)
	v_mfma_f32_32x32x16_bf16 v[48:63], v[86:89], v[120:123], v[48:63]
	v_mfma_f32_32x32x16_bf16 v[0:15], v[90:93], v[110:113], v[0:15]
	v_mfma_f32_32x32x16_bf16 v[16:31], v[90:93], v[120:123], v[16:31]
	ds_read_b128 v[86:89], v64 offset:192
	ds_read_b128 v[90:93], v64 offset:8896
	ds_read_b128 v[110:113], v107 offset:35008
	ds_read_b128 v[120:123], v107 offset:43712
	s_waitcnt lgkmcnt(1)
	v_mfma_f32_32x32x16_bf16 v[32:47], v[86:89], v[110:113], v[32:47]
	s_waitcnt lgkmcnt(0)
	v_mfma_f32_32x32x16_bf16 v[48:63], v[86:89], v[120:123], v[48:63]
	v_mfma_f32_32x32x16_bf16 v[0:15], v[90:93], v[110:113], v[0:15]
	v_mfma_f32_32x32x16_bf16 v[16:31], v[90:93], v[120:123], v[16:31]
	ds_read_b128 v[86:89], v64 offset:224
	ds_read_b128 v[90:93], v64 offset:8928
	ds_read_b128 v[110:113], v107 offset:35040
	ds_read_b128 v[120:123], v107 offset:43744
	s_waitcnt lgkmcnt(0)
	s_barrier
; DI int crow(int r, int h) { return (r & 3) + 8 * (r >> 2) + 4 * h; }
; DI float fmax_fast(float a, float b) { float r; asm("v_max_f32 %0, %1, %2" : "=v"(r) : "v"(a), "v"(b)); return r; }
; __device__ void phase_peerq(const Params& p, int bid, int nb, char* lds, const TileMap& tm) {
;     ...
;     }
;     __syncthreads();
; #pragma unroll
;     for (int i = 0; i < 2; ++i)
; #pragma unroll
;       for (int j = 0; j < 2; ++j)
; #pragma unroll
;         for (int r = 0; r < 16; ++r)
;           scs[(64 * wm + 32 * i + crow(r, h)) * SC_LD + 64 * wn + 32 * j + l31] = acc[i][j][r];
;     __syncthreads();
;     {
;       const int row = tid >> 1, half = tid & 1;
;       float* rp = scs + row * SC_LD + half;
;       const size_t ob = ((size_t)(m0 + row) * 16 + hp) * 16;
;       float gm[8];
; #pragma unroll
;       for (int g = 0; g < 8; ++g) {
;         float m = rp[16 * g];
; #pragma unroll
;         for (int j = 1; j < 8; ++j) m = fmax_fast(m, rp[16 * g + 2 * j]);
;         gm[g] = m;
;       }
	v_mfma_f32_32x32x16_bf16 v[32:47], v[86:89], v[110:113], v[32:47]
	v_mfma_f32_32x32x16_bf16 v[48:63], v[86:89], v[120:123], v[48:63]
	s_nop 11
	ds_write2_b32 v84, v32, v48 offset1:32
	ds_write2_b32 v84, v33, v49 offset0:130 offset1:162
	v_mfma_f32_32x32x16_bf16 v[0:15], v[90:93], v[110:113], v[0:15]
	v_add_u32_e32 v32, 0x400, v84
	ds_write2_b32 v32, v34, v50 offset0:4 offset1:36
	ds_write2_b32 v32, v35, v51 offset0:134 offset1:166
	v_add_u32_e32 v32, 0x1000, v84
	ds_write2_b32 v32, v36, v52 offset0:16 offset1:48
	ds_write2_b32 v32, v37, v53 offset0:146 offset1:178
	v_add_u32_e32 v32, 0x1400, v84
	ds_write2_b32 v32, v38, v54 offset0:20 offset1:52
	ds_write2_b32 v32, v39, v55 offset0:150 offset1:182
	v_add_u32_e32 v32, 0x2000, v84
	v_mfma_f32_32x32x16_bf16 v[16:31], v[90:93], v[120:123], v[16:31]
	ds_write2_b32 v32, v40, v56 offset0:32 offset1:64
	ds_write2_b32 v32, v41, v57 offset0:162 offset1:194
	v_add_u32_e32 v32, 0x2400, v84
	ds_write2_b32 v32, v42, v58 offset0:36 offset1:68
	ds_write2_b32 v32, v43, v59 offset0:166 offset1:198
	v_add_u32_e32 v32, 0x3000, v84
	ds_write2_b32 v32, v44, v60 offset0:48 offset1:80
	ds_write2_b32 v32, v45, v61 offset0:178 offset1:210
	v_add_u32_e32 v32, 0x3400, v84
	ds_write2_b32 v32, v46, v62 offset0:52 offset1:84
	ds_write2_b32 v32, v47, v63 offset0:182 offset1:214
	v_add_u32_e32 v32, 0x4000, v84
	ds_write2_b32 v32, v0, v16 offset0:64 offset1:96
	ds_write2_b32 v32, v1, v17 offset0:194 offset1:226
	v_add_u32_e32 v0, 0x4400, v84
	ds_write2_b32 v0, v2, v18 offset0:68 offset1:100
	ds_write2_b32 v0, v3, v19 offset0:198 offset1:230
	v_add_u32_e32 v0, 0x5000, v84
	ds_write2_b32 v0, v4, v20 offset0:80 offset1:112
	ds_write2_b32 v0, v5, v21 offset0:210 offset1:242
	v_add_u32_e32 v0, 0x5400, v84
	ds_write2_b32 v0, v6, v22 offset0:84 offset1:116
	ds_write2_b32 v0, v7, v23 offset0:214 offset1:246
	v_add_u32_e32 v0, 0x6000, v84
	ds_write2_b32 v0, v8, v24 offset0:96 offset1:128
	v_add_u32_e32 v0, 0x6200, v84
	ds_write2_b32 v0, v9, v25 offset0:98 offset1:130
	v_add_u32_e32 v0, 0x6400, v84
	ds_write2_b32 v0, v10, v26 offset0:100 offset1:132
	v_add_u32_e32 v0, 0x6600, v84
	ds_write2_b32 v0, v11, v27 offset0:102 offset1:134
	v_add_u32_e32 v0, 0x7000, v84
	ds_write2_b32 v0, v12, v28 offset0:112 offset1:144
	v_add_u32_e32 v0, 0x7200, v84
	ds_write2_b32 v0, v13, v29 offset0:114 offset1:146
	v_add_u32_e32 v0, 0x7400, v84
	ds_write2_b32 v0, v14, v30 offset0:116 offset1:148
	v_add_u32_e32 v0, 0x7600, v84
	ds_write2_b32 v0, v15, v31 offset0:118 offset1:150
	s_waitcnt lgkmcnt(0)
	s_barrier
	s_setprio 0
	ds_read2_b32 v[2:3], v97 offset1:2
	ds_read2_b32 v[4:5], v97 offset0:4 offset1:6
	ds_read2_b32 v[6:7], v97 offset0:8 offset1:10
	ds_read2_b32 v[8:9], v97 offset0:12 offset1:14
	s_waitcnt lgkmcnt(3)
	v_max_f32 v1, v2, v3
	s_waitcnt lgkmcnt(2)
	v_max_f32 v1, v1, v4
	ds_read2_b32 v[2:3], v97 offset0:16 offset1:18
	v_max_f32 v1, v1, v5
	v_add_u32_e32 v0, s3, v94
	s_waitcnt lgkmcnt(2)
	v_max_f32 v1, v1, v6
	s_nop 0
	v_max_f32 v1, v1, v7
	s_waitcnt lgkmcnt(1)
	v_max_f32 v1, v1, v8
	s_nop 0
	v_max_f32 v6, v1, v9
	s_waitcnt lgkmcnt(0)
	v_max_f32 v1, v2, v3
	ds_read2_b32 v[2:3], v97 offset0:20 offset1:22
	s_waitcnt lgkmcnt(0)
	v_max_f32 v1, v1, v2
	s_nop 0
	v_max_f32 v1, v1, v3
	ds_read2_b32 v[2:3], v97 offset0:24 offset1:26
	s_waitcnt lgkmcnt(0)
	v_max_f32 v1, v1, v2
	s_nop 0
	v_max_f32 v1, v1, v3
	ds_read2_b32 v[2:3], v97 offset0:28 offset1:30
	s_waitcnt lgkmcnt(0)
	v_max_f32 v1, v1, v2
	s_nop 0
	v_max_f32 v7, v1, v3
	ds_read2_b32 v[2:3], v97 offset0:32 offset1:34
	s_waitcnt lgkmcnt(0)
	v_max_f32 v1, v2, v3
	ds_read2_b32 v[2:3], v97 offset0:36 offset1:38
	s_waitcnt lgkmcnt(0)
	v_max_f32 v1, v1, v2
	s_nop 0
	v_max_f32 v1, v1, v3
	ds_read2_b32 v[2:3], v97 offset0:40 offset1:42
	s_waitcnt lgkmcnt(0)
	v_max_f32 v1, v1, v2
	s_nop 0
	v_max_f32 v1, v1, v3
	ds_read2_b32 v[2:3], v97 offset0:44 offset1:46
	s_waitcnt lgkmcnt(0)
	v_max_f32 v1, v1, v2
	s_nop 0
	v_max_f32 v8, v1, v3
	ds_read2_b32 v[2:3], v97 offset0:48 offset1:50
	s_waitcnt lgkmcnt(0)
	v_max_f32 v1, v2, v3
	ds_read2_b32 v[2:3], v97 offset0:52 offset1:54
	s_waitcnt lgkmcnt(0)
	v_max_f32 v1, v1, v2
	s_nop 0
	v_max_f32 v1, v1, v3
	ds_read2_b32 v[2:3], v97 offset0:56 offset1:58
	s_waitcnt lgkmcnt(0)
	v_max_f32 v1, v1, v2
	s_nop 0
	v_max_f32 v1, v1, v3
	ds_read2_b32 v[2:3], v97 offset0:60 offset1:62
	s_waitcnt lgkmcnt(0)
	v_max_f32 v1, v1, v2
	s_nop 0
	v_max_f32 v9, v1, v3
	ds_read2_b32 v[2:3], v97 offset0:64 offset1:66
	s_waitcnt lgkmcnt(0)
	v_max_f32 v1, v2, v3
	ds_read2_b32 v[2:3], v97 offset0:68 offset1:70
	s_waitcnt lgkmcnt(0)
	v_max_f32 v1, v1, v2
	s_nop 0
	v_max_f32 v1, v1, v3
	ds_read2_b32 v[2:3], v97 offset0:72 offset1:74
	s_waitcnt lgkmcnt(0)
	v_max_f32 v1, v1, v2
	s_nop 0
	v_max_f32 v1, v1, v3
	ds_read2_b32 v[2:3], v97 offset0:76 offset1:78
	s_waitcnt lgkmcnt(0)
	v_max_f32 v1, v1, v2
	s_nop 0
	v_max_f32 v10, v1, v3
	ds_read2_b32 v[2:3], v97 offset0:80 offset1:82
	s_waitcnt lgkmcnt(0)
	v_max_f32 v1, v2, v3
	ds_read2_b32 v[2:3], v97 offset0:84 offset1:86
	s_waitcnt lgkmcnt(0)
	v_max_f32 v1, v1, v2
	s_nop 0
	v_max_f32 v1, v1, v3
	ds_read2_b32 v[2:3], v97 offset0:88 offset1:90
	s_waitcnt lgkmcnt(0)
	v_max_f32 v1, v1, v2
	s_nop 0
	v_max_f32 v1, v1, v3
	ds_read2_b32 v[2:3], v97 offset0:92 offset1:94
	s_waitcnt lgkmcnt(0)
	v_max_f32 v1, v1, v2
	s_nop 0
	v_max_f32 v11, v1, v3
	ds_read2_b32 v[2:3], v97 offset0:96 offset1:98
	s_waitcnt lgkmcnt(0)
	v_max_f32 v1, v2, v3
	ds_read2_b32 v[2:3], v97 offset0:100 offset1:102
	s_waitcnt lgkmcnt(0)
	v_max_f32 v1, v1, v2
	s_nop 0
	v_max_f32 v1, v1, v3
	ds_read2_b32 v[2:3], v97 offset0:104 offset1:106
	s_waitcnt lgkmcnt(0)
	v_max_f32 v1, v1, v2
	s_nop 0
	v_max_f32 v1, v1, v3
	ds_read2_b32 v[2:3], v97 offset0:108 offset1:110
	s_waitcnt lgkmcnt(0)
	v_max_f32 v1, v1, v2
	s_nop 0
	v_max_f32 v12, v1, v3
	ds_read2_b32 v[2:3], v97 offset0:112 offset1:114
	s_waitcnt lgkmcnt(0)
	v_max_f32 v1, v2, v3
	ds_read2_b32 v[2:3], v97 offset0:116 offset1:118
	s_waitcnt lgkmcnt(0)
	v_max_f32 v1, v1, v2
	s_nop 0
	v_max_f32 v1, v1, v3
	ds_read2_b32 v[2:3], v97 offset0:120 offset1:122
	s_waitcnt lgkmcnt(0)
	v_max_f32 v1, v1, v2
	s_nop 0
	v_max_f32 v1, v1, v3
	ds_read2_b32 v[2:3], v97 offset0:124 offset1:126
	s_waitcnt lgkmcnt(0)
	v_max_f32 v1, v1, v2
	s_nop 0
	v_max_f32 v13, v1, v3
	v_ashrrev_i32_e32 v1, 31, v0
	v_lshlrev_b64 v[0:1], 10, v[0:1]
	v_lshl_add_u64 v[4:5], s[0:1], 0, v[0:1]
	s_branch .LBB0_455
